# P3->P4 barrier XCD-local too (P3 units permuted so a row tile's retention rows come from its own class); verdict cached at the P2->P3 barrier
# baseline (speedup 1.0000x reference)
; DI unsigned xb_ld(unsigned* p) { return __hip_atomic_load(p, __ATOMIC_RELAXED, __HIP_MEMORY_SCOPE_AGENT); }
; DI void xcd_barrier_complete(unsigned* bar, unsigned x, unsigned& nloc, unsigned& nx) {
;   const unsigned G = gridDim.x * gridDim.y * gridDim.z;
;   unsigned sum, cnt, mine, sp = 0u;
;   for (;;) {
;     sum = 0u; cnt = 0u; mine = 0u;
; #pragma unroll
;     for (unsigned j = 0; j < 16; ++j) { const unsigned c = xb_ld(&bar[XB_XCNT(j)]); sum += c; cnt += (c > 0u) ? 1u : 0u; mine = (j == x) ? c : mine; }
;     if (sum == G) break;
;     __builtin_amdgcn_s_sleep(1);
;     if ((++sp & 255u) == 0u) { if (xb_ld(&bar[XB_TMO])) break; if (sp > XB_SPIN_CAP) { atomicAdd(&bar[XB_TMO], 1u); break; } }
;   }
;   nloc = mine > 0u ? mine : 1u; nx = cnt > 0u ? cnt : 1u;
; }
; DI void xcd_barrier(const XcdBarrier& b) {
;   asm volatile("s_waitcnt vmcnt(0)" ::: "memory");
;   __syncthreads();
;   if (threadIdx.x == 0) {
;     unsigned* bar = b.bar;
;     __builtin_amdgcn_s_waitcnt(0);
;     unsigned nloc = b.st[0], nx = b.st[1];
;     if (nloc == 0u) { xcd_barrier_complete(bar, b.x, nloc, nx); b.st[0] = nloc; b.st[1] = nx; }
.LBB0_674:
	s_waitcnt vmcnt(0)
	s_barrier
	s_and_saveexec_b64 s[6:7], s[94:95]
	s_cbranch_execz .LBB0_726
	s_add_i32 s8, 0, 0x23ff0
	s_waitcnt vmcnt(27)
	v_mov_b32_e32 v0, s8
	s_waitcnt vmcnt(0) expcnt(0) lgkmcnt(0)
	v_mov_b32_e32 v253, 0x1e7e1300
	global_load_dwordx4 v[240:243], v253, s[26:27] sc1
	global_load_dwordx4 v[244:247], v253, s[26:27] offset:16 sc1
	ds_read_b32 v2, v0
	s_add_i32 s8, 0, 0x23ff4
	v_mov_b32_e32 v0, s8
	ds_read_b32 v0, v0
	s_waitcnt lgkmcnt(1)
	v_cmp_ne_u32_e32 vcc, 0, v2
	s_cbranch_vccnz .LBB0_690
	v_readlane_b32 s8, v250, 0
	s_mul_i32 s18, s29, s8
	s_add_u32 s8, s26, 0x1e7e1200
	s_addc_u32 s9, s27, 0
	s_add_u32 s10, s26, 0x1e7e1400
	s_addc_u32 s11, s27, 0
	s_add_u32 s12, s26, 0x1e7e1500
	s_addc_u32 s13, s27, 0
	s_add_u32 s14, s26, 0x1e7e1600
	s_addc_u32 s15, s27, 0
	s_add_u32 s16, s26, 0x1e7e1700
	s_addc_u32 s17, s27, 0
	s_add_u32 s20, s26, 0x1e7e1800
	s_addc_u32 s21, s27, 0
	s_add_u32 s22, s26, 0x1e7e1900
	s_addc_u32 s23, s27, 0
	s_add_u32 s40, s26, 0x1e7e1a00
	s_addc_u32 s41, s27, 0
	s_add_u32 s42, s26, 0x1e7e1b00
	s_addc_u32 s43, s27, 0
	s_add_u32 s44, s26, 0x1e7e1c00
	s_addc_u32 s45, s27, 0
	s_add_u32 s46, s26, 0x1e7e1d00
	s_addc_u32 s47, s27, 0
	s_add_u32 s48, s26, 0x1e7e1e00
	s_addc_u32 s49, s27, 0
	s_add_u32 s50, s26, 0x1e7e1f00
	s_addc_u32 s51, s27, 0
	s_add_u32 s52, s26, 0x1e7e2000
	s_addc_u32 s53, s27, 0
	s_add_u32 s54, s26, 0x1e7e2100
	s_addc_u32 s55, s27, 0
	s_add_u32 s56, s26, 0x1e7e2200
	s_addc_u32 s57, s27, 0
	s_add_u32 s58, s26, 0x1e7e2300
	s_mul_i32 s18, s18, s28
	s_addc_u32 s59, s27, 0
	s_mov_b32 s19, 1
	v_mov_b32_e32 v16, 0
	s_branch .LBB0_678

; #define LAS __attribute__((address_space(3)))
;     ...
;   int tid_ = threadIdx.x; asm volatile("" : "+v"(tid_)); const int tid = tid_, wid = __builtin_amdgcn_readfirstlane(tid >> 6), lane = tid & 63, fr = lane & 15, fq = lane >> 4;
;   const bf16_t* Qr = (const bf16_t*)(ws + OFF_QR); const bf16_t* Kr = (const bf16_t*)(ws + OFF_KR); const bf16_t* Vrt = (const bf16_t*)(ws + OFF_VRT);
;   const bf16_t* RT = (const bf16_t*)p.out;
;   bf16_t* G = (bf16_t*)(ws + OFF_G);
;     ...
;   for (int u = blockIdx.x; u < 1024; u += gridDim.x) {
;     const int bh = u >> 6, c = u & 63, h = bh & 3, b = bh >> 2;
;     const float gam = exp2f(lg2gamma(h));
;     {
;       const u32x4* qg = (const u32x4*)(Qr + (long)(bh * 64 + c) * 16384); const u32x4* kg = (const u32x4*)(Kr + (long)(bh * 64 + c) * 16384);
;       u32x4 qv[4], kv[4];
; #pragma unroll
;       for (int i = 0; i < 4; ++i) { qv[i] = qg[tid + i * NTHREADS]; kv[i] = kg[tid + i * NTHREADS]; }
; #pragma unroll
;       for (int i = 0; i < 4; ++i) { *(LAS u32x4*)(shm + RO_Q + (tid + i * NTHREADS) * 16) = qv[i]; *(LAS u32x4*)(shm + RO_K + (tid + i * NTHREADS) * 16) = kv[i]; }
;     }
;     bf16x8 rf[2][4], vf[2][4];
;     {
;       const bf16_t* rp = RT + (long)(bh * 64 + c) * 32768 + (2 * wid) * 2048 + lane * 8;
;       const bf16_t* vp = Vrt + (long)(bh * 64 + c) * 32768 + (2 * wid) * 2048 + lane * 8;
.LBB0_726:
	s_or_b64 exec, exec, s[6:7]
	s_and_saveexec_b64 s[98:99], s[94:95]
	v_add_u32_e32 v248, -1, v240
	v_and_b32_e32 v248, v248, v240
	v_add_u32_e32 v249, -1, v241
	v_and_b32_e32 v249, v249, v241
	v_or_b32_e32 v248, v248, v249
	v_add_u32_e32 v249, -1, v242
	v_and_b32_e32 v249, v249, v242
	v_or_b32_e32 v248, v248, v249
	v_add_u32_e32 v249, -1, v243
	v_and_b32_e32 v249, v249, v243
	v_or_b32_e32 v248, v248, v249
	v_add_u32_e32 v249, -1, v244
	v_and_b32_e32 v249, v249, v244
	v_or_b32_e32 v248, v248, v249
	v_add_u32_e32 v249, -1, v245
	v_and_b32_e32 v249, v249, v245
	v_or_b32_e32 v248, v248, v249
	v_add_u32_e32 v249, -1, v246
	v_and_b32_e32 v249, v249, v246
	v_or_b32_e32 v248, v248, v249
	v_add_u32_e32 v249, -1, v247
	v_and_b32_e32 v249, v249, v247
	v_or_b32_e32 v248, v248, v249
	v_cmp_eq_u32_e32 vcc, 0, v248
	s_nop 1
	v_cndmask_b32_e64 v249, 0, 1, vcc
	v_mov_b32_e32 v253, 0x23ff8
	ds_write_b32 v253, v249
	s_or_b64 exec, exec, s[98:99]
	s_add_u32 s22, s26, 0x2300000
	s_addc_u32 s23, s27, 0
	s_waitcnt vmcnt(27) lgkmcnt(0)
	v_mov_b32_e32 v0, v194
	s_add_u32 s68, s26, 0xc300000
	s_barrier
	s_addc_u32 s69, s27, 0
	s_andn2_b64 vcc, exec, s[0:1]
	v_readfirstlane_b32 s0, v0
	s_cbranch_vccnz .LBB0_755
	s_ashr_i32 s12, s0, 6
	s_lshl_b32 s10, s12, 12
	s_ashr_i32 s11, s10, 31
	s_add_i32 s1, 0, 0x18000
	s_lshl_b64 s[6:7], s[10:11], 1
	s_add_u32 s8, s24, s6
	s_addc_u32 s9, s25, s7
	v_and_b32_e32 v1, 63, v0
	s_waitcnt vmcnt(14)
	v_mov_b32_e32 v91, 0
	s_add_u32 s6, s3, s6
	v_lshlrev_b32_e32 v88, 4, v1
	v_mov_b32_e32 v89, v91
	s_addc_u32 s7, s66, s7
	s_lshl_b32 s3, s12, 4
	s_ashr_i32 s0, s0, 31
	s_waitcnt vmcnt(12)
	v_lshl_add_u64 v[94:95], s[6:7], 0, v[88:89]
	s_or_b32 s6, s3, 15
	s_lshr_b32 s0, s0, 27
	v_and_b32_e32 v3, 15, v0
	s_add_i32 s0, s6, s0
	v_lshl_add_u64 v[92:93], s[8:9], 0, v[88:89]
	s_ashr_i32 s39, s0, 5
	v_or_b32_e32 v89, s3, v3
	s_add_i32 s3, s10, 0
	s_cmpk_gt_i32 s6, 0xffe0
	s_movk_i32 s0, 0x80
	s_cselect_b64 s[40:41], -1, 0
	v_cmp_gt_u32_e64 s[6:7], 16, v1
	v_cmp_gt_i32_e64 s[8:9], s0, v0
	v_lshlrev_b32_e32 v1, 3, v0
	s_add_i32 s11, 0, 0x1a000
	s_mul_i32 s0, s12, 0x2800
	s_waitcnt vmcnt(6)
	v_add_u32_e32 v121, s1, v1
	v_add_u32_e32 v122, s11, v1
	s_add_i32 s13, s0, 0
	v_and_b32_e32 v4, 24, v1
	v_and_b32_e32 v1, 3, v0
	v_lshrrev_b32_e32 v2, 1, v0
	v_lshl_add_u32 v13, v1, 4, s13
	v_lshlrev_b32_e32 v6, 3, v1
	v_ashrrev_i32_e32 v1, 31, v0
	v_lshlrev_b32_e32 v7, 4, v0
	v_and_b32_e32 v9, 24, v2
	v_lshlrev_b32_e32 v2, 8, v0
	v_bfe_u32 v10, v0, 2, 4
	v_lshlrev_b64 v[0:1], 4, v[0:1]
	v_lshlrev_b32_e32 v5, 3, v3
	s_lshl_b32 s30, s12, 10
	v_add_u32_e32 v11, s13, v9
	s_lshl_b32 s0, s12, 5
	v_lshl_add_u64 v[96:97], s[22:23], 0, v[0:1]
	v_lshl_add_u64 v[0:1], s[26:27], 0, v[0:1]
	s_mov_b64 s[12:13], 0x4300000
	v_add_u32_e32 v131, 0, v88
	v_add_u32_e32 v120, s1, v5
	v_add_u32_e32 v123, s11, v5
	v_lshlrev_b32_e32 v8, 10, v10
	v_or_b32_e32 v5, 16, v10
	v_lshl_add_u64 v[98:99], v[0:1], 0, s[12:13]
	v_add_u32_e32 v0, s10, v131
	s_ashr_i32 s1, s0, 31
	v_and_b32_e32 v2, 0x3c00, v2
	v_mul_u32_u24_e32 v15, 0x50, v10
	v_mul_u32_u24_e32 v3, 0x50, v3
	v_mul_u32_u24_e32 v17, 0x50, v5
	v_lshlrev_b32_e32 v10, 10, v5
	v_or_b32_e32 v12, 0x8000, v8
	v_or_b32_e32 v14, 0xc000, v8
	v_or_b32_e32 v16, 0x10000, v8
	v_or_b32_e32 v18, 0x14000, v8
	v_or_b32_e32 v20, 0x18000, v8
	v_or_b32_e32 v22, 0x1c000, v8
	v_add_u32_e32 v132, 0x10000, v0
	v_mbcnt_lo_u32_b32 v0, -1, 0
	s_mov_b32 s18, 0
	s_mov_b32 s19, 0x18000
	s_waitcnt vmcnt(4)
	v_add_u32_e32 v124, 0x80, v123
	v_add_u32_e32 v125, 0x100, v123
	v_add_u32_e32 v126, 0x180, v123
	v_add_u32_e32 v127, 0x200, v123
	v_add_u32_e32 v128, 0x280, v123
	v_add_u32_e32 v129, 0x300, v123
	v_add_u32_e32 v130, 0x380, v123
	s_mov_b32 s31, 0x8000
	s_mov_b32 s38, 0x10000
	s_add_i32 s39, s39, 1
	v_or_b32_e32 v133, 7, v9
	v_add_u32_e32 v134, 0x8000, v131
	v_add_u32_e32 v135, 0, v7
	s_movk_i32 s43, 0x1000
	v_mbcnt_hi_u32_b32 v136, -1, v0
	s_mov_b32 s42, 0x3b800000
	v_add_u32_e32 v137, v11, v3
	s_lshl_b64 s[44:45], s[0:1], 1
	v_lshlrev_b32_e32 v90, 1, v4
	v_lshlrev_b32_e32 v100, 1, v2
	s_mov_b32 s48, 0x20000
	s_mov_b32 s49, 0x28000
	s_mov_b32 s50, 0x30000
	s_mov_b32 s51, 0x38000
	v_lshlrev_b32_e32 v102, 1, v6
	v_add_u32_e32 v138, v13, v15
	v_lshlrev_b32_e32 v104, 1, v8
	v_add_u32_e32 v139, v13, v17
	v_lshlrev_b32_e32 v106, 1, v10
	v_lshlrev_b32_e32 v108, 1, v12
	v_lshlrev_b32_e32 v110, 1, v14
	v_lshlrev_b32_e32 v112, 1, v16
	v_lshlrev_b32_e32 v114, 1, v18
	v_lshlrev_b32_e32 v116, 1, v20
	v_lshlrev_b32_e32 v118, 1, v22
	v_mov_b32_e32 v140, 0x3f7f0000
	v_mov_b32_e32 v141, 0x3f7e0000
	s_and_b32 s46, s2, 0xffffffc0
	s_and_b32 s98, s2, 7
	s_lshl_b32 s98, s98, 1
	s_or_b32 s46, s46, s98
	s_bfe_u32 s98, s2, 0x10003
	s_or_b32 s46, s46, s98
	s_and_b32 s98, s2, 0x30
	s_or_b32 s46, s46, s98
	s_branch .LBB0_729

; DI unsigned xb_ld(unsigned* p) { return __hip_atomic_load(p, __ATOMIC_RELAXED, __HIP_MEMORY_SCOPE_AGENT); }
; DI unsigned xb_add(unsigned* p, unsigned v) { return __hip_atomic_fetch_add(p, v, __ATOMIC_RELAXED, __HIP_MEMORY_SCOPE_AGENT); }
; #define XB_SPIN(cond, bar) do { unsigned _sp = 0; while (cond) { __builtin_amdgcn_s_sleep(1); \
;     if ((++_sp & 255u) == 0u) { if (xb_ld(&(bar)[XB_TMO])) break; if (_sp > XB_SPIN_CAP) { atomicAdd(&(bar)[XB_TMO], 1u); break; } } } } while (0)
; DI void xcd_barrier(const XcdBarrier& b) {
;     ...
;     const unsigned old = xb_add(&bar[XB_XSUB(b.x)], 1u);
;     const unsigned gen = old / nloc;
;     if (old + 1u == (gen + 1u) * nloc) {
;       __builtin_amdgcn_fence(__ATOMIC_RELEASE, "agent");
;       asm volatile("s_waitcnt vmcnt(0)" ::: "memory");
;       const unsigned og = xb_add(&bar[XB_TOP], 1u);
;       const unsigned tg = og / nx;
;       if (og + 1u == (tg + 1u) * nx) xb_add(&bar[XB_TOPGEN], 1u);
;       else XB_SPIN(xb_ld(&bar[XB_TOPGEN]) == tg, bar);
;       __builtin_amdgcn_fence(__ATOMIC_ACQUIRE, "agent");
;       xb_add(&bar[XB_XGEN(b.x)], 1u);
.LBB0_787:
	s_andn2_saveexec_b64 s[8:9], s[8:9]
	s_cbranch_execz .LBB0_807
	s_mov_b64 s[8:9], exec
	v_mov_b32_e32 v253, 0x23ff8
	ds_read_b32 v252, v253
	buffer_wbl2 sc1
	s_waitcnt lgkmcnt(0)
	s_waitcnt vmcnt(0)
	v_cmp_ne_u32_e32 vcc, 0, v252
	s_cbranch_vccnz .LBB0_804
	v_mbcnt_lo_u32_b32 v1, s8, 0
	v_mbcnt_hi_u32_b32 v1, s9, v1
	v_cmp_eq_u32_e32 vcc, 0, v1
	s_and_saveexec_b64 s[10:11], vcc
	s_cbranch_execz .LBB0_790
	s_bcnt1_i32_b64 s3, s[8:9]
	v_mov_b32_e32 v2, 0x1e7e4000
	v_mov_b32_e32 v3, s3
	global_atomic_add v2, v2, v3, s[26:27] offset:1024 sc0
